# attention local stage: the K row loads are issued before the end-of-ctx-phase barrier (only the LDS writes need it)
# baseline (speedup 1.0000x reference)
; #define LAS __attribute__((address_space(3)))
; __device__ __forceinline__ int kswz(int key) { return ((key >> 1) & 1) | (((key >> 3) & 3) << 1); }
; __device__ __forceinline__ void phase_mixer(const Params& p, LAS unsigned char* lds, int l, bool with_ctx, int G, int tid, int wave, int lane, int rep_attn, int rep_pool) {
;     ...
;             const int tok0 = b * SEQ + rs0 * 64;
;             const bf16_t* ksrc = PB + (size_t)(tok0 + (tid >> 3)) * PBW + 1024 + h * 64 + (tid & 7) * 8;
;             u32x4 kreg[9], vreg[9];
; #pragma unroll
;             for (int ps = 0; ps < 9; ++ps) { const int idx = ps * 512 + tid, d = idx / 72, ch = idx - d * 72;
;                 kreg[ps] = *(const u32x4*)(ksrc + (size_t)(ps * 64) * PBW);
;                 vreg[ps] = *(const u32x4*)(VT + (size_t)(h * 64 + d) * VTP + tok0 + ch * 8); }
;             __builtin_amdgcn_sched_barrier(0);
; #pragma unroll
;             for (int ps = 0; ps < 9; ++ps) { const int key = ps * 64 + (tid >> 3), idx = ps * 512 + tid, d = idx / 72, ch = idx - d * 72;
;                 *(LAS u32x4*)(lds + AT_KL + key * 128 + ((((tid & 7) ^ kswz(key))) << 4)) = kreg[ps];
;                 *(LAS u32x4*)(lds + AT_VL + d * AT_VLP + ((ch ^ (d & 15)) << 4)) = vreg[ps]; }
.LBB0_301:
	v_sub_u32_e64 v24, s71, 4 clamp
	v_min_u32_e32 v26, 56, v24
	v_lshlrev_b32_e32 v24, 6, v26
	v_or_b32_e32 v24, s76, v24
	v_add_u32_e32 v25, v24, v109
	v_mov_b64_e32 v[30:31], s[0:1]
	v_mad_i64_i32 v[30:31], s[68:69], v25, s58, v[30:31]
	s_lshl_b32 s30, s70, 1
	v_lshl_add_u64 v[30:31], v[30:31], 0, s[30:31]
	v_lshl_add_u64 v[70:71], v[30:31], 0, v[156:157]
	s_mov_b32 s68, 0x30000
	v_add_co_u32_e32 v38, vcc, s68, v70
	s_nop 0
	v_addc_co_u32_e32 v39, vcc, 0, v71, vcc
	s_mov_b32 s68, 0x60000
	v_add_co_u32_e32 v46, vcc, s68, v70
	s_nop 0
	v_addc_co_u32_e32 v47, vcc, 0, v71, vcc
	s_mov_b32 s68, 0x90000
	v_add_co_u32_e32 v54, vcc, s68, v70
	s_nop 0
	v_addc_co_u32_e32 v55, vcc, 0, v71, vcc
	s_mov_b32 s68, 0xc0000
	v_add_co_u32_e32 v62, vcc, s68, v70
	s_nop 0
	v_addc_co_u32_e32 v63, vcc, 0, v71, vcc
	s_mov_b32 s68, 0xf0000
	v_add_co_u32_e32 v100, vcc, s68, v70
	v_addc_co_u32_e32 v101, vcc, 0, v71, vcc
	s_mov_b32 s68, 0x120000
	global_load_dwordx4 v[30:33], v[70:71], off offset:2048
	s_nop 0
	s_nop 0
	global_load_dwordx4 v[38:41], v[38:39], off offset:2048
	s_nop 0
	s_nop 0
	global_load_dwordx4 v[46:49], v[46:47], off offset:2048
	s_nop 0
	s_nop 0
	global_load_dwordx4 v[54:57], v[54:55], off offset:2048
	s_nop 0
	s_nop 0
	global_load_dwordx4 v[62:65], v[62:63], off offset:2048
	s_nop 0
	s_nop 0
	global_load_dwordx4 v[100:103], v[100:101], off offset:2048
	s_nop 0
	v_add_co_u32_e32 v104, vcc, s68, v70
	s_nop 0
	v_addc_co_u32_e32 v105, vcc, 0, v71, vcc
	s_mov_b32 s68, 0x150000
	global_load_dwordx4 v[170:173], v[104:105], off offset:2048
	s_nop 0
	v_add_co_u32_e32 v104, vcc, s68, v70
	s_nop 0
	v_addc_co_u32_e32 v105, vcc, 0, v71, vcc
	s_mov_b32 s68, 0x180000
	v_add_co_u32_e32 v70, vcc, s68, v70
	v_addc_co_u32_e32 v71, vcc, 0, v71, vcc
	global_load_dwordx4 v[178:181], v[104:105], off offset:2048
	s_nop 0
	global_load_dwordx4 v[186:189], v[70:71], off offset:2048
	s_barrier
	s_waitcnt vmcnt(8)
	ds_write_b128 v111, v[30:33]
	s_waitcnt vmcnt(7)
	ds_write_b128 v111, v[38:41] offset:8192
	s_waitcnt vmcnt(6)
	ds_write_b128 v111, v[46:49] offset:16384
	s_waitcnt vmcnt(5)
	ds_write_b128 v111, v[54:57] offset:24576
	s_waitcnt vmcnt(4)
	ds_write_b128 v111, v[62:65] offset:32768
	s_waitcnt vmcnt(3)
	ds_write_b128 v111, v[100:103] offset:40960
	s_waitcnt vmcnt(2)
	ds_write_b128 v111, v[170:173] offset:49152
	s_waitcnt vmcnt(1)
	ds_write_b128 v111, v[178:181] offset:57344
	s_waitcnt vmcnt(0)
	ds_write_b128 v125, v[186:189]
	s_mov_b32 s80, 0x3a800000
	s_mov_b64 s[68:69], exec
	s_cmp_eq_u32 s61, s2
	s_cbranch_scc1 .Lrpb_load
	s_and_b32 s32, s3, 7
	s_cmp_eq_u32 s32, 0
	s_cbranch_scc1 .LBB0_296
